# att26 = att14 + s_setprio 2 over the attention row-max / decision chain (from the first hoisted P.V MFMA to the head of the P.V half), s_setprio 0 after
# baseline (speedup 1.0000x reference)
.LBB0_300:
	s_lshl_b32 s0, s0, 1
	v_add_u32_e32 v0, s0, v248
	ds_read_b64_tr_b16 v[2:3], v0 offset:24576
	ds_read_b64_tr_b16 v[4:5], v0 offset:25088
	s_waitcnt lgkmcnt(9)
	v_mfma_f32_32x32x16_bf16 v[144:159], v[220:223], v[188:191], v[80:95]
	v_add_f32_e32 v6, v112, v113
	v_add_f32_e32 v6, v114, v6
	v_add_f32_e32 v6, v115, v6
	v_add_f32_e32 v6, v116, v6
	v_add_f32_e32 v10, v117, v6
	v_cvt_pk_bf16_f32 v180, v112, v113
	v_cvt_pk_bf16_f32 v181, v114, v115
	ds_read_b64_tr_b16 v[6:7], v0 offset:28672
	ds_read_b64_tr_b16 v[8:9], v0 offset:29184
	s_waitcnt lgkmcnt(10)
	v_mfma_f32_32x32x16_bf16 v[128:143], v[216:219], v[188:191], v[80:95]
	v_add_f32_e32 v10, v118, v10
	v_add_f32_e32 v10, v119, v10
	v_add_f32_e32 v10, v120, v10
	v_add_f32_e32 v14, v121, v10
	v_cvt_pk_bf16_f32 v182, v116, v117
	v_cvt_pk_bf16_f32 v183, v118, v119
	ds_read_b64_tr_b16 v[10:11], v0 offset:25600
	ds_read_b64_tr_b16 v[12:13], v0 offset:26112
	s_waitcnt lgkmcnt(11)
	v_mfma_f32_32x32x16_bf16 v[144:159], v[212:215], v[184:187], v[144:159]
	v_add_f32_e32 v14, v122, v14
	v_add_f32_e32 v14, v123, v14
	v_add_f32_e32 v14, v124, v14
	v_add_f32_e32 v14, v125, v14
	v_cvt_pk_bf16_f32 v172, v120, v121
	v_cvt_pk_bf16_f32 v173, v122, v123
	ds_read_b64_tr_b16 v[112:113], v0 offset:29696
	ds_read_b64_tr_b16 v[114:115], v0 offset:30208
	s_waitcnt lgkmcnt(12)
	v_mfma_f32_32x32x16_bf16 v[128:143], v[208:211], v[184:187], v[128:143]
	v_add_f32_e32 v14, v126, v14
	v_add_f32_e32 v14, v127, v14
	v_add_f32_e32 v14, v96, v14
	v_add_f32_e32 v14, v97, v14
	v_cvt_pk_bf16_f32 v174, v124, v125
	v_cvt_pk_bf16_f32 v175, v126, v127
	ds_read_b64_tr_b16 v[116:117], v0 offset:26624
	ds_read_b64_tr_b16 v[118:119], v0 offset:27136
	s_waitcnt lgkmcnt(13)
	v_mfma_f32_32x32x16_bf16 v[144:159], v[204:207], v[176:179], v[144:159]
	v_add_f32_e32 v14, v98, v14
	v_add_f32_e32 v14, v99, v14
	v_add_f32_e32 v14, v100, v14
	v_add_f32_e32 v14, v101, v14
	v_cvt_pk_bf16_f32 v164, v96, v97
	v_cvt_pk_bf16_f32 v165, v98, v99
	ds_read_b64_tr_b16 v[96:97], v0 offset:30720
	ds_read_b64_tr_b16 v[98:99], v0 offset:31232
	s_waitcnt lgkmcnt(14)
	v_mfma_f32_32x32x16_bf16 v[128:143], v[200:203], v[176:179], v[128:143]
	v_add_f32_e32 v14, v102, v14
	v_add_f32_e32 v14, v103, v14
	v_add_f32_e32 v14, v104, v14
	v_add_f32_e32 v14, v105, v14
	v_cvt_pk_bf16_f32 v166, v100, v101
	v_cvt_pk_bf16_f32 v167, v102, v103
	ds_read_b64_tr_b16 v[100:101], v0 offset:27648
	ds_read_b64_tr_b16 v[102:103], v0 offset:28160
	s_waitcnt lgkmcnt(14)
	v_mfma_f32_32x32x16_bf16 v[144:159], v[196:199], v[168:171], v[144:159]
	v_add_f32_e32 v14, v106, v14
	v_add_f32_e32 v14, v107, v14
	v_add_f32_e32 v14, v108, v14
	v_add_f32_e32 v14, v109, v14
	v_cvt_pk_bf16_f32 v160, v104, v105
	v_cvt_pk_bf16_f32 v161, v106, v107
	ds_read_b64_tr_b16 v[104:105], v0 offset:31744
	ds_read_b64_tr_b16 v[106:107], v0 offset:32256
	v_mfma_f32_32x32x16_bf16 v[128:143], v[192:195], v[168:171], v[128:143]
	v_add_f32_e32 v14, v110, v14
	v_add_f32_e32 v14, v111, v14
	v_add_f32_e32 v214, v250, v14
	v_cvt_pk_bf16_f32 v162, v108, v109
	v_cvt_pk_bf16_f32 v163, v110, v111
	s_add_i32 s0, s38, s46
	s_mov_b32 s1, m0
	s_mov_b32 m0, s0
	s_nop 0
	global_load_lds_dwordx4 v253, s[98:99]
	s_mov_b32 m0, s1
	s_setprio 2
	s_waitcnt lgkmcnt(14)
	v_mfma_f32_32x32x16_bf16 v[16:31], v[180:183], v[2:5], v[16:31]
	v_max_f32_e32 v108, v144, v145
	v_max3_f32 v109, v146, v147, v129
	v_max3_f32 v108, v108, v128, v130
	v_max3_f32 v108, v108, v131, v148
	v_max3_f32 v109, v109, v150, v151
	v_max3_f32 v108, v108, v149, v132
	s_waitcnt lgkmcnt(12)
	v_mfma_f32_32x32x16_bf16 v[32:47], v[180:183], v[6:9], v[32:47]
	v_max3_f32 v109, v109, v134, v135
	v_max3_f32 v108, v108, v133, v152
	v_max3_f32 v109, v109, v154, v155
	v_max3_f32 v108, v108, v153, v136
	v_max3_f32 v109, v109, v138, v139
	v_max3_f32 v108, v108, v137, v156
	s_waitcnt lgkmcnt(10)
	v_mfma_f32_32x32x16_bf16 v[16:31], v[172:175], v[10:13], v[16:31]
	v_max3_f32 v109, v109, v158, v159
	v_max3_f32 v108, v108, v157, v140
	v_max3_f32 v109, v109, v142, v143
	v_max3_f32 v108, v108, v141, v109
	v_mov_b32_e32 v109, v108
	s_nop 1
	v_permlane32_swap_b32_e32 v108, v109
	v_max_f32_e32 v108, v108, v109
	v_cmp_lt_f32_e32 vcc, s25, v108
	s_cmp_lg_u64 vcc, 0
	s_cselect_b64 s[78:79], -1, 0
	s_cbranch_vccnz .LBB0_308
.LBB0_301:
	s_setprio 0
	v_exp_f32_e32 v144, v144
	v_exp_f32_e32 v145, v145
	ds_read_b64_tr_b16 v[2:3], v0 offset:32768
	ds_read_b64_tr_b16 v[4:5], v0 offset:33280
	v_exp_f32_e32 v146, v146
	v_exp_f32_e32 v147, v147
	ds_read_b64_tr_b16 v[6:7], v0 offset:36864
	ds_read_b64_tr_b16 v[8:9], v0 offset:37376
	s_lshl_b32 s0, s19, 1
	s_add_i32 s0, s0, s47
	s_mov_b32 s1, m0
	s_mov_b32 m0, s0
	s_nop 0
	global_load_lds_dwordx4 v255, s[100:101]
	s_mov_b32 m0, s1
	v_exp_f32_e32 v148, v148
	v_exp_f32_e32 v149, v149
	ds_read_b64_tr_b16 v[10:11], v0 offset:33792
	ds_read_b64_tr_b16 v[12:13], v0 offset:34304
	s_addk_i32 s0, 0x1f80
	s_mov_b32 s1, m0
	s_mov_b32 m0, s0
	s_nop 0
	global_load_lds_dwordx4 v255, s[100:101] offset:128
	s_mov_b32 m0, s1
	s_add_u32 s98, s98, 0x20000
	s_addc_u32 s99, s99, 0
	s_add_u32 s100, s100, 0x20000
	s_addc_u32 s101, s101, 0
	s_waitcnt lgkmcnt(14)
	v_mfma_f32_32x32x16_bf16 v[32:47], v[172:175], v[112:115], v[32:47]
	v_exp_f32_e32 v150, v150
	v_exp_f32_e32 v151, v151
	ds_read_b64_tr_b16 v[108:109], v0 offset:37888
	ds_read_b64_tr_b16 v[110:111], v0 offset:38400
	s_waitcnt lgkmcnt(14)
	v_mfma_f32_32x32x16_bf16 v[16:31], v[164:167], v[116:119], v[16:31]
	v_exp_f32_e32 v152, v152
	v_exp_f32_e32 v153, v153
	ds_read_b64_tr_b16 v[112:113], v0 offset:34816
	ds_read_b64_tr_b16 v[114:115], v0 offset:35328
	s_waitcnt lgkmcnt(14)
	v_mfma_f32_32x32x16_bf16 v[32:47], v[164:167], v[96:99], v[32:47]
	v_exp_f32_e32 v154, v154
	v_exp_f32_e32 v155, v155
	ds_read_b64_tr_b16 v[116:117], v0 offset:38912
	ds_read_b64_tr_b16 v[118:119], v0 offset:39424
	s_waitcnt lgkmcnt(14)
	v_mfma_f32_32x32x16_bf16 v[16:31], v[160:163], v[100:103], v[16:31]
	v_exp_f32_e32 v156, v156
	v_exp_f32_e32 v157, v157
	ds_read_b64_tr_b16 v[100:101], v0 offset:35840
	ds_read_b64_tr_b16 v[102:103], v0 offset:36352
	s_waitcnt lgkmcnt(14)
	v_mfma_f32_32x32x16_bf16 v[32:47], v[160:163], v[104:107], v[32:47]
	v_exp_f32_e32 v158, v158
	v_exp_f32_e32 v159, v159
	ds_read_b64_tr_b16 v[104:105], v0 offset:39936
	ds_read_b64_tr_b16 v[106:107], v0 offset:40448
	s_waitcnt lgkmcnt(14)
	v_mfma_f32_32x32x16_bf16 v[48:63], v[180:183], v[2:5], v[48:63]
	v_exp_f32_e32 v128, v128
	v_exp_f32_e32 v129, v129
	s_waitcnt lgkmcnt(12)
	v_mfma_f32_32x32x16_bf16 v[64:79], v[180:183], v[6:9], v[64:79]
	v_exp_f32_e32 v130, v130
	v_exp_f32_e32 v131, v131
	v_add_u32_e32 v0, s19, v247
	ds_read_b128 v[96:99], v0
	ds_read_b128 v[204:207], v0 offset:512
	s_waitcnt lgkmcnt(12)
	v_mfma_f32_32x32x16_bf16 v[48:63], v[172:175], v[10:13], v[48:63]
	v_exp_f32_e32 v132, v132
	v_exp_f32_e32 v133, v133
	ds_read_b128 v[208:211], v0 offset:2048
	ds_read_b128 v[200:203], v0 offset:2560
	s_waitcnt lgkmcnt(12)
	v_mfma_f32_32x32x16_bf16 v[64:79], v[172:175], v[108:111], v[64:79]
	v_exp_f32_e32 v134, v134
	v_exp_f32_e32 v135, v135
	ds_read_b128 v[196:199], v0 offset:4096
	ds_read_b128 v[10:13], v0 offset:4608
	s_waitcnt lgkmcnt(12)
	v_mfma_f32_32x32x16_bf16 v[48:63], v[164:167], v[112:115], v[48:63]
	v_exp_f32_e32 v136, v136
	v_exp_f32_e32 v137, v137
	ds_read_b128 v[6:9], v0 offset:6144
	ds_read_b128 v[2:5], v0 offset:6656
	s_waitcnt lgkmcnt(12)
	v_mfma_f32_32x32x16_bf16 v[64:79], v[164:167], v[116:119], v[64:79]
	v_exp_f32_e32 v138, v138
	v_exp_f32_e32 v139, v139
	s_waitcnt lgkmcnt(10)
	v_mfma_f32_32x32x16_bf16 v[48:63], v[160:163], v[100:103], v[48:63]
	v_exp_f32_e32 v140, v140
	v_exp_f32_e32 v141, v141
	s_waitcnt lgkmcnt(8)
	v_mfma_f32_32x32x16_bf16 v[64:79], v[160:163], v[104:107], v[64:79]
	v_exp_f32_e32 v142, v142
	v_exp_f32_e32 v143, v143
	s_waitcnt vmcnt(3) lgkmcnt(0)
	s_barrier
	s_andn2_b64 vcc, exec, s[78:79]
	v_add_u32_e32 v0, s45, v249
	s_cbranch_vccnz .LBB0_303
	s_waitcnt lgkmcnt(0)
	ds_read_b128 v[100:103], v0 offset:96
	ds_read_b128 v[104:107], v0 offset:64
	ds_read_b128 v[108:111], v0 offset:32
	ds_read_b128 v[112:115], v0
	s_waitcnt lgkmcnt(3)
	v_pk_mul_f32 v[28:29], v[28:29], v[100:101]
	s_waitcnt lgkmcnt(2)
	v_pk_mul_f32 v[24:25], v[24:25], v[104:105]
	s_waitcnt lgkmcnt(1)
	v_pk_mul_f32 v[20:21], v[20:21], v[108:109]
	v_pk_mul_f32 v[30:31], v[30:31], v[102:103]
	v_pk_mul_f32 v[26:27], v[26:27], v[106:107]
	v_pk_mul_f32 v[22:23], v[22:23], v[110:111]
	s_waitcnt lgkmcnt(0)
	v_pk_mul_f32 v[18:19], v[18:19], v[114:115]
	v_pk_mul_f32 v[16:17], v[16:17], v[112:113]
	v_pk_mul_f32 v[44:45], v[44:45], v[100:101]
	v_pk_mul_f32 v[40:41], v[40:41], v[104:105]
	v_pk_mul_f32 v[36:37], v[36:37], v[108:109]
	v_pk_mul_f32 v[46:47], v[46:47], v[102:103]
	v_pk_mul_f32 v[42:43], v[42:43], v[106:107]
	v_pk_mul_f32 v[38:39], v[38:39], v[110:111]
	v_pk_mul_f32 v[34:35], v[34:35], v[114:115]
	v_pk_mul_f32 v[32:33], v[32:33], v[112:113]
	v_pk_mul_f32 v[60:61], v[60:61], v[100:101]
	v_pk_mul_f32 v[56:57], v[56:57], v[104:105]
	v_pk_mul_f32 v[52:53], v[52:53], v[108:109]
	v_pk_mul_f32 v[62:63], v[62:63], v[102:103]
	v_pk_mul_f32 v[58:59], v[58:59], v[106:107]
	v_pk_mul_f32 v[54:55], v[54:55], v[110:111]
	v_pk_mul_f32 v[50:51], v[50:51], v[114:115]
	v_pk_mul_f32 v[48:49], v[48:49], v[112:113]
	v_pk_mul_f32 v[76:77], v[76:77], v[100:101]
	v_pk_mul_f32 v[72:73], v[72:73], v[104:105]
	v_pk_mul_f32 v[68:69], v[68:69], v[108:109]
	v_pk_mul_f32 v[78:79], v[78:79], v[102:103]
	v_pk_mul_f32 v[74:75], v[74:75], v[106:107]
	v_pk_mul_f32 v[70:71], v[70:71], v[110:111]
	v_pk_mul_f32 v[66:67], v[66:67], v[114:115]
	v_pk_mul_f32 v[64:65], v[64:65], v[112:113]
.LBB0_303:
	s_add_i32 s0, s19, 0x2000
	s_cmpk_lg_i32 s19, 0x4000
	s_cselect_b32 s50, s0, 0
	s_lshl_b32 s0, s38, 1
	v_add_u32_e32 v215, s0, v248
	ds_read_b64_tr_b16 v[192:193], v215 offset:24576
	ds_read_b64_tr_b16 v[194:195], v215 offset:25088
	s_waitcnt lgkmcnt(9)
	v_mfma_f32_32x32x16_bf16 v[112:127], v[96:99], v[188:191], v[80:95]
	v_add_f32_e32 v100, v144, v145
	v_add_f32_e32 v100, v146, v100
	v_add_f32_e32 v100, v147, v100
	v_add_f32_e32 v100, v148, v100
	v_add_f32_e32 v100, v149, v100
	v_cvt_pk_bf16_f32 v180, v144, v145
	v_cvt_pk_bf16_f32 v181, v146, v147
	ds_read_b64_tr_b16 v[144:145], v215 offset:28672
	ds_read_b64_tr_b16 v[146:147], v215 offset:29184
	v_add_f32_e32 v96, v150, v100
	v_add_f32_e32 v96, v151, v96
	v_add_f32_e32 v96, v152, v96
	v_add_f32_e32 v160, v153, v96
	s_waitcnt lgkmcnt(10)
	v_mfma_f32_32x32x16_bf16 v[96:111], v[204:207], v[188:191], v[80:95]
	v_cvt_pk_bf16_f32 v182, v148, v149
	v_cvt_pk_bf16_f32 v183, v150, v151
	ds_read_b64_tr_b16 v[148:149], v215 offset:25600
	ds_read_b64_tr_b16 v[150:151], v215 offset:26112
	s_waitcnt lgkmcnt(11)
	v_mfma_f32_32x32x16_bf16 v[112:127], v[208:211], v[184:187], v[112:127]
	v_add_f32_e32 v160, v154, v160
	v_add_f32_e32 v160, v155, v160
	v_add_f32_e32 v160, v156, v160
	v_add_f32_e32 v160, v157, v160
	v_cvt_pk_bf16_f32 v172, v152, v153
	v_cvt_pk_bf16_f32 v173, v154, v155
	ds_read_b64_tr_b16 v[152:153], v215 offset:29696
	ds_read_b64_tr_b16 v[154:155], v215 offset:30208
	s_waitcnt lgkmcnt(12)
	v_mfma_f32_32x32x16_bf16 v[96:111], v[200:203], v[184:187], v[96:111]
	v_add_f32_e32 v160, v158, v160
	v_add_f32_e32 v160, v159, v160
	v_add_f32_e32 v160, v128, v160
	v_add_f32_e32 v160, v129, v160
	v_cvt_pk_bf16_f32 v174, v156, v157
	v_cvt_pk_bf16_f32 v175, v158, v159
	ds_read_b64_tr_b16 v[156:157], v215 offset:26624
	ds_read_b64_tr_b16 v[158:159], v215 offset:27136
	s_waitcnt lgkmcnt(13)
	v_mfma_f32_32x32x16_bf16 v[112:127], v[196:199], v[176:179], v[112:127]
	v_add_f32_e32 v160, v130, v160
	v_add_f32_e32 v160, v131, v160
	v_add_f32_e32 v160, v132, v160
	v_add_f32_e32 v160, v133, v160
	v_cvt_pk_bf16_f32 v164, v128, v129
	v_cvt_pk_bf16_f32 v165, v130, v131
	ds_read_b64_tr_b16 v[128:129], v215 offset:30720
	ds_read_b64_tr_b16 v[130:131], v215 offset:31232
	s_waitcnt lgkmcnt(14)
	v_mfma_f32_32x32x16_bf16 v[96:111], v[10:13], v[176:179], v[96:111]
	v_add_f32_e32 v10, v134, v160
	v_add_f32_e32 v10, v135, v10
	v_add_f32_e32 v10, v136, v10
	v_add_f32_e32 v160, v137, v10
	v_cvt_pk_bf16_f32 v166, v132, v133
	v_cvt_pk_bf16_f32 v167, v134, v135
	ds_read_b64_tr_b16 v[10:11], v215 offset:27648
	ds_read_b64_tr_b16 v[12:13], v215 offset:28160
	s_waitcnt lgkmcnt(14)
	v_mfma_f32_32x32x16_bf16 v[112:127], v[6:9], v[168:171], v[112:127]
	v_add_f32_e32 v6, v138, v160
	v_add_f32_e32 v6, v139, v6
	v_add_f32_e32 v6, v140, v6
	v_add_f32_e32 v132, v141, v6
	v_cvt_pk_bf16_f32 v160, v136, v137
	v_cvt_pk_bf16_f32 v161, v138, v139
	ds_read_b64_tr_b16 v[6:7], v215 offset:31744
	ds_read_b64_tr_b16 v[8:9], v215 offset:32256
	v_mfma_f32_32x32x16_bf16 v[96:111], v[2:5], v[168:171], v[96:111]
	v_add_f32_e32 v2, v142, v132
	v_add_f32_e32 v2, v143, v2
	v_add_f32_e32 v250, v214, v2
	v_cvt_pk_bf16_f32 v162, v140, v141
	v_cvt_pk_bf16_f32 v163, v142, v143
	s_add_i32 s0, s19, s46
	s_mov_b32 s1, m0
	s_mov_b32 m0, s0
	s_nop 0
	global_load_lds_dwordx4 v253, s[98:99]
	s_mov_b32 m0, s1
	s_setprio 2
	s_waitcnt lgkmcnt(14)
	v_mfma_f32_32x32x16_bf16 v[16:31], v[180:183], v[192:195], v[16:31]
	v_max_f32_e32 v2, v112, v113
	v_max3_f32 v3, v114, v115, v97
	v_max3_f32 v2, v2, v96, v98
	v_max3_f32 v2, v2, v99, v116
	v_max3_f32 v3, v3, v118, v119
	v_max3_f32 v2, v2, v117, v100
	s_waitcnt lgkmcnt(12)
	v_mfma_f32_32x32x16_bf16 v[32:47], v[180:183], v[144:147], v[32:47]
	v_max3_f32 v3, v3, v102, v103
	v_max3_f32 v2, v2, v101, v120
	v_max3_f32 v3, v3, v122, v123
	v_max3_f32 v2, v2, v121, v104
	v_max3_f32 v3, v3, v106, v107
	v_max3_f32 v2, v2, v105, v124
	s_waitcnt lgkmcnt(10)
	v_mfma_f32_32x32x16_bf16 v[16:31], v[172:175], v[148:151], v[16:31]
	v_max3_f32 v3, v3, v126, v127
	v_max3_f32 v2, v2, v125, v108
	v_max3_f32 v3, v3, v110, v111
	v_max3_f32 v2, v2, v109, v3
	v_mov_b32_e32 v3, v2
	s_nop 1
	v_permlane32_swap_b32_e32 v2, v3
	v_max_f32_e32 v2, v2, v3
	v_cmp_lt_f32_e32 vcc, s25, v2
	s_cmp_lg_u64 vcc, 0
	s_cselect_b64 s[78:79], -1, 0
	s_cbranch_vccnz .LBB0_311
.LBB0_304:
	s_setprio 0
	v_exp_f32_e32 v112, v112
	v_exp_f32_e32 v113, v113
	ds_read_b64_tr_b16 v[2:3], v215 offset:32768
	ds_read_b64_tr_b16 v[4:5], v215 offset:33280
	v_exp_f32_e32 v114, v114
	v_exp_f32_e32 v115, v115
	ds_read_b64_tr_b16 v[132:133], v215 offset:36864
	ds_read_b64_tr_b16 v[134:135], v215 offset:37376
	s_lshl_b32 s0, s50, 1
	s_add_i32 s18, s0, s47
	s_mov_b32 s0, m0
	s_mov_b32 m0, s18
	s_nop 0
	global_load_lds_dwordx4 v255, s[100:101]
	s_mov_b32 m0, s0
	v_exp_f32_e32 v116, v116
	v_exp_f32_e32 v117, v117
	ds_read_b64_tr_b16 v[136:137], v215 offset:33792
	ds_read_b64_tr_b16 v[138:139], v215 offset:34304
	s_add_i32 s0, s18, 0x1f80
	s_mov_b32 s1, m0
	s_mov_b32 m0, s0
	s_nop 0
	global_load_lds_dwordx4 v255, s[100:101] offset:128
	s_mov_b32 m0, s1
	s_add_u32 s98, s98, 0x20000
	s_addc_u32 s99, s99, 0
	s_add_u32 s100, s100, 0x20000
	s_addc_u32 s101, s101, 0
	s_waitcnt lgkmcnt(14)
	v_mfma_f32_32x32x16_bf16 v[32:47], v[172:175], v[152:155], v[32:47]
	v_exp_f32_e32 v118, v118
	v_exp_f32_e32 v119, v119
	ds_read_b64_tr_b16 v[140:141], v215 offset:37888
	ds_read_b64_tr_b16 v[142:143], v215 offset:38400
	s_waitcnt lgkmcnt(14)
	v_mfma_f32_32x32x16_bf16 v[16:31], v[164:167], v[156:159], v[16:31]
	v_exp_f32_e32 v120, v120
	v_exp_f32_e32 v121, v121
	ds_read_b64_tr_b16 v[144:145], v215 offset:34816
	ds_read_b64_tr_b16 v[146:147], v215 offset:35328
	s_waitcnt lgkmcnt(14)
	v_mfma_f32_32x32x16_bf16 v[32:47], v[164:167], v[128:131], v[32:47]
	v_exp_f32_e32 v122, v122
	v_exp_f32_e32 v123, v123
	ds_read_b64_tr_b16 v[128:129], v215 offset:38912
	ds_read_b64_tr_b16 v[130:131], v215 offset:39424
	s_waitcnt lgkmcnt(14)
	v_mfma_f32_32x32x16_bf16 v[16:31], v[160:163], v[10:13], v[16:31]
	v_exp_f32_e32 v124, v124
	v_exp_f32_e32 v125, v125
	ds_read_b64_tr_b16 v[10:11], v215 offset:35840
	ds_read_b64_tr_b16 v[12:13], v215 offset:36352
	s_waitcnt lgkmcnt(14)
	v_mfma_f32_32x32x16_bf16 v[32:47], v[160:163], v[6:9], v[32:47]
	v_exp_f32_e32 v126, v126
	v_exp_f32_e32 v127, v127
	ds_read_b64_tr_b16 v[6:7], v215 offset:39936
	ds_read_b64_tr_b16 v[8:9], v215 offset:40448
	s_waitcnt lgkmcnt(14)
	v_mfma_f32_32x32x16_bf16 v[48:63], v[180:183], v[2:5], v[48:63]
	v_exp_f32_e32 v96, v96
	v_exp_f32_e32 v97, v97
	s_waitcnt lgkmcnt(12)
	v_mfma_f32_32x32x16_bf16 v[64:79], v[180:183], v[132:135], v[64:79]
	v_exp_f32_e32 v98, v98
	v_exp_f32_e32 v99, v99
	v_add_u32_e32 v2, s50, v247
	ds_read_b128 v[220:223], v2
	ds_read_b128 v[216:219], v2 offset:512
	s_waitcnt lgkmcnt(12)
	v_mfma_f32_32x32x16_bf16 v[48:63], v[172:175], v[136:139], v[48:63]
	v_exp_f32_e32 v100, v100
	v_exp_f32_e32 v101, v101
	ds_read_b128 v[212:215], v2 offset:2048
	ds_read_b128 v[208:211], v2 offset:2560
	s_waitcnt lgkmcnt(12)
	v_mfma_f32_32x32x16_bf16 v[64:79], v[172:175], v[140:143], v[64:79]
	v_exp_f32_e32 v102, v102
	v_exp_f32_e32 v103, v103
	ds_read_b128 v[204:207], v2 offset:4096
	ds_read_b128 v[200:203], v2 offset:4608
	s_waitcnt lgkmcnt(12)
	v_mfma_f32_32x32x16_bf16 v[48:63], v[164:167], v[144:147], v[48:63]
	v_exp_f32_e32 v104, v104
	v_exp_f32_e32 v105, v105
	ds_read_b128 v[196:199], v2 offset:6144
	ds_read_b128 v[192:195], v2 offset:6656
	s_waitcnt lgkmcnt(12)
	v_mfma_f32_32x32x16_bf16 v[64:79], v[164:167], v[128:131], v[64:79]
	v_exp_f32_e32 v106, v106
	v_exp_f32_e32 v107, v107
	s_waitcnt lgkmcnt(10)
	v_mfma_f32_32x32x16_bf16 v[48:63], v[160:163], v[10:13], v[48:63]
	v_exp_f32_e32 v108, v108
	v_exp_f32_e32 v109, v109
	s_waitcnt lgkmcnt(8)
	v_mfma_f32_32x32x16_bf16 v[64:79], v[160:163], v[6:9], v[64:79]
	v_exp_f32_e32 v110, v110
	v_exp_f32_e32 v111, v111
	s_waitcnt vmcnt(3) lgkmcnt(0)
	s_barrier
	s_andn2_b64 vcc, exec, s[78:79]
	s_cbranch_vccnz .LBB0_306
	s_waitcnt lgkmcnt(0)
	ds_read_b128 v[2:5], v0 offset:96
	ds_read_b128 v[6:9], v0 offset:64
	ds_read_b128 v[10:13], v0 offset:32
	ds_read_b128 v[128:131], v0
	s_waitcnt lgkmcnt(3)
	v_pk_mul_f32 v[28:29], v[28:29], v[2:3]
	s_waitcnt lgkmcnt(2)
	v_pk_mul_f32 v[24:25], v[24:25], v[6:7]
	s_waitcnt lgkmcnt(1)
	v_pk_mul_f32 v[20:21], v[20:21], v[10:11]
	v_pk_mul_f32 v[30:31], v[30:31], v[4:5]
	v_pk_mul_f32 v[26:27], v[26:27], v[8:9]
	v_pk_mul_f32 v[22:23], v[22:23], v[12:13]
	s_waitcnt lgkmcnt(0)
	v_pk_mul_f32 v[18:19], v[18:19], v[130:131]
	v_pk_mul_f32 v[16:17], v[16:17], v[128:129]
	v_pk_mul_f32 v[44:45], v[44:45], v[2:3]
	v_pk_mul_f32 v[40:41], v[40:41], v[6:7]
	v_pk_mul_f32 v[36:37], v[36:37], v[10:11]
	v_pk_mul_f32 v[46:47], v[46:47], v[4:5]
	v_pk_mul_f32 v[42:43], v[42:43], v[8:9]
	v_pk_mul_f32 v[38:39], v[38:39], v[12:13]
	v_pk_mul_f32 v[34:35], v[34:35], v[130:131]
	v_pk_mul_f32 v[32:33], v[32:33], v[128:129]
	v_pk_mul_f32 v[60:61], v[60:61], v[2:3]
	v_pk_mul_f32 v[56:57], v[56:57], v[6:7]
	v_pk_mul_f32 v[52:53], v[52:53], v[10:11]
	v_pk_mul_f32 v[62:63], v[62:63], v[4:5]
	v_pk_mul_f32 v[58:59], v[58:59], v[8:9]
	v_pk_mul_f32 v[54:55], v[54:55], v[12:13]
	v_pk_mul_f32 v[50:51], v[50:51], v[130:131]
	v_pk_mul_f32 v[48:49], v[48:49], v[128:129]
	v_pk_mul_f32 v[76:77], v[76:77], v[2:3]
	v_pk_mul_f32 v[72:73], v[72:73], v[6:7]
	v_pk_mul_f32 v[68:69], v[68:69], v[10:11]
	v_pk_mul_f32 v[78:79], v[78:79], v[4:5]
	v_pk_mul_f32 v[74:75], v[74:75], v[8:9]
	v_pk_mul_f32 v[70:71], v[70:71], v[12:13]
	v_pk_mul_f32 v[66:67], v[66:67], v[130:131]
	v_pk_mul_f32 v[64:65], v[64:65], v[128:129]
